# LN phases (8,11,15,18): row stores (XA f32, HB bf16, d_out) marked nt (streaming)
# speedup vs baseline: 1.0111x; 1.0085x over previous
.LBB0_1053:
	s_or_b64 exec, exec, s[2:3]
	s_waitcnt vmcnt(0)
	v_add_f32_e32 v54, v34, v35
	v_add_f32_e32 v69, v36, v37
	v_add_f32_e32 v54, v54, v69
	v_add_f32_e32 v69, v38, v39
	v_add_f32_e32 v71, v40, v41
	v_add_f32_e32 v54, 0, v54
	v_add_f32_e32 v69, v69, v71
	v_add_f32_e32 v54, v54, v69
	v_add_f32_e32 v69, v42, v43
	v_add_f32_e32 v71, v44, v45
	v_mov_b32_e32 v78, v47
	v_mov_b32_e32 v79, v48
	v_mov_b32_e32 v80, v46
	v_mov_b32_e32 v81, v49
	v_add_f32_e32 v69, v69, v71
	v_pk_add_f32 v[78:79], v[78:79], v[80:81]
	v_add_f32_e32 v54, v54, v69
	v_add_f32_e32 v69, v78, v79
	v_add_f32_e32 v54, v54, v69
	v_cmp_gt_i32_e32 vcc, s20, v50
	v_mov_b32_e32 v77, v55
	v_add_f32_dpp v54, v54, v54 quad_perm:[1,0,3,2] row_mask:0xf bank_mask:0xf bound_ctrl:1
	v_mov_b32_e32 v73, v55
	v_lshl_add_u64 v[74:75], v[64:65], 0, v[74:75]
	v_add_f32_dpp v54, v54, v54 quad_perm:[2,3,0,1] row_mask:0xf bank_mask:0xf bound_ctrl:1
	s_nop 1
	v_add_f32_dpp v54, v54, v54 row_ror:4 row_mask:0xf bank_mask:0xf bound_ctrl:1
	s_nop 1
	v_add_f32_dpp v54, v54, v54 row_ror:8 row_mask:0xf bank_mask:0xf bound_ctrl:1
	ds_bpermute_b32 v69, v1, v54
	s_waitcnt lgkmcnt(0)
	v_add_f32_e32 v54, v54, v69
	ds_bpermute_b32 v69, v53, v54
	s_waitcnt lgkmcnt(0)
	v_add_f32_e32 v71, v54, v69
	v_cndmask_b32_e64 v54, v85, 0, vcc
	v_lshl_add_u64 v[78:79], s[58:59], 0, v[54:55]
	v_lshl_add_u64 v[106:107], v[78:79], 0, s[14:15]
	v_lshl_add_u64 v[102:103], v[78:79], 0, s[16:17]
	v_lshl_add_u64 v[78:79], v[106:107], 0, v[76:77]
	v_lshl_add_u64 v[80:81], v[102:103], 0, v[76:77]
	global_load_dwordx4 v[76:79], v[78:79], off
	s_nop 0
	global_load_dwordx4 v[80:83], v[80:81], off
	v_fmamk_f32 v35, v71, 0xba800000, v35
	v_fmamk_f32 v34, v71, 0xba800000, v34
	v_fmamk_f32 v37, v71, 0xba800000, v37
	v_fmac_f32_e32 v36, 0xba800000, v71
	v_pk_mul_f32 v[86:87], v[36:37], v[36:37]
	v_pk_mul_f32 v[88:89], v[34:35], v[34:35]
	v_fmamk_f32 v39, v71, 0xba800000, v39
	v_pk_mov_b32 v[90:91], v[88:89], v[86:87] op_sel:[1,0]
	v_mov_b32_e32 v89, v87
	v_pk_add_f32 v[86:87], v[90:91], v[88:89]
	v_fmamk_f32 v38, v71, 0xba800000, v38
	v_fmamk_f32 v41, v71, 0xba800000, v41
	v_fmac_f32_e32 v40, 0xba800000, v71
	v_pk_add_f32 v[94:95], v[86:87], v[86:87] op_sel_hi:[0,1]
	v_pk_mul_f32 v[86:87], v[40:41], v[40:41]
	v_pk_mul_f32 v[88:89], v[38:39], v[38:39]
	v_mov_b32_e32 v69, v55
	v_pk_mov_b32 v[90:91], v[88:89], v[86:87] op_sel:[1,0]
	v_mov_b32_e32 v89, v87
	v_pk_add_f32 v[86:87], v[90:91], v[88:89]
	v_lshl_add_u64 v[90:91], v[102:103], 0, v[68:69]
	v_pk_add_f32 v[96:97], v[86:87], v[86:87] op_sel_hi:[0,1]
	v_lshl_add_u64 v[86:87], v[106:107], 0, v[68:69]
	global_load_dwordx4 v[86:89], v[86:87], off
	s_nop 0
	global_load_dwordx4 v[90:93], v[90:91], off
	v_fmamk_f32 v42, v71, 0xba800000, v42
	v_fmamk_f32 v43, v71, 0xba800000, v43
	v_fmac_f32_e32 v44, 0xba800000, v71
	v_mul_f32_e32 v54, v42, v42
	v_fmamk_f32 v45, v71, 0xba800000, v45
	v_pk_fma_f32 v[98:99], v[42:43], v[42:43], v[54:55] op_sel_hi:[1,1,0]
	v_mul_f32_e32 v54, v44, v44
	v_pk_fma_f32 v[100:101], v[44:45], v[44:45], v[54:55] op_sel_hi:[1,1,0]
	v_fmamk_f32 v49, v71, 0xba800000, v49
	v_fmamk_f32 v48, v71, 0xba800000, v48
	v_fmamk_f32 v47, v71, 0xba800000, v47
	v_fmac_f32_e32 v46, 0xba800000, v71
	v_mul_f32_e32 v98, v46, v46
	v_mul_f32_e32 v100, v47, v47
	v_mul_f32_e32 v94, v48, v48
	v_mul_f32_e32 v96, v49, v49
	v_pk_add_f32 v[98:99], v[98:99], v[100:101]
	v_pk_add_f32 v[94:95], v[94:95], v[96:97]
	v_mov_b32_e32 v71, v55
	v_pk_add_f32 v[94:95], v[98:99], v[94:95]
	v_lshl_add_u64 v[98:99], v[102:103], 0, v[70:71]
	v_add_f32_e32 v54, v94, v95
	v_lshl_add_u64 v[94:95], v[106:107], 0, v[70:71]
	global_load_dwordx4 v[94:97], v[94:95], off
	s_nop 0
	global_load_dwordx4 v[98:101], v[98:99], off
	v_lshl_add_u64 v[102:103], v[102:103], 0, v[72:73]
	global_load_dwordx4 v[102:105], v[102:103], off
	v_lshl_add_u64 v[106:107], v[106:107], 0, v[72:73]
	global_load_dwordx4 v[106:109], v[106:107], off
	v_add_f32_dpp v54, v54, v54 quad_perm:[1,0,3,2] row_mask:0xf bank_mask:0xf bound_ctrl:1
	s_waitcnt vmcnt(6)
	v_pk_add_f32 v[80:81], v[80:81], 1.0 op_sel_hi:[1,0]
	v_add_f32_dpp v54, v54, v54 quad_perm:[2,3,0,1] row_mask:0xf bank_mask:0xf bound_ctrl:1
	v_pk_add_f32 v[82:83], v[82:83], 1.0 op_sel_hi:[1,0]
	s_nop 0
	v_add_f32_dpp v54, v54, v54 row_ror:4 row_mask:0xf bank_mask:0xf bound_ctrl:1
	s_nop 1
	v_add_f32_dpp v54, v54, v54 row_ror:8 row_mask:0xf bank_mask:0xf bound_ctrl:1
	ds_bpermute_b32 v69, v1, v54
	s_waitcnt lgkmcnt(0)
	v_add_f32_e32 v54, v54, v69
	ds_bpermute_b32 v69, v53, v54
	s_waitcnt lgkmcnt(0)
	v_add_f32_e32 v54, v54, v69
	v_fmamk_f32 v54, v54, 0x3a800000, v84
	v_mul_f32_e32 v69, 0x4b800000, v54
	v_cmp_gt_f32_e32 vcc, s21, v54
	s_nop 1
	v_cndmask_b32_e32 v54, v54, v69, vcc
	v_rsq_f32_e32 v54, v54
	s_nop 0
	v_mul_f32_e32 v69, 0x45800000, v54
	v_cndmask_b32_e32 v54, v54, v69, vcc
	v_pk_mul_f32 v[34:35], v[34:35], v[54:55] op_sel_hi:[1,0]
	v_pk_mul_f32 v[36:37], v[36:37], v[54:55] op_sel_hi:[1,0]
	v_pk_fma_f32 v[34:35], v[2:3], v[34:35], v[6:7]
	v_pk_fma_f32 v[36:37], v[4:5], v[36:37], v[8:9]
	global_store_dwordx4 v[74:75], v[34:37], off nt
	s_nop 1
	v_pk_fma_f32 v[34:35], v[80:81], v[34:35], v[76:77]
	v_pk_fma_f32 v[36:37], v[82:83], v[36:37], v[78:79]
	s_nop 0
	s_nop 0
	s_nop 0
	s_nop 0
	s_nop 0
	v_cvt_pk_bf16_f32 v34, v34, v35
	s_nop 0
	s_nop 0
	s_nop 0
	s_nop 0
	s_nop 0
	v_cvt_pk_bf16_f32 v35, v36, v37
	v_lshlrev_b64 v[36:37], 11, v[50:51]
	v_lshl_add_u64 v[76:77], v[66:67], 0, v[36:37]
	global_store_dwordx2 v[76:77], v[34:35], off nt
	v_pk_mul_f32 v[34:35], v[38:39], v[54:55] op_sel_hi:[1,0]
	v_pk_mul_f32 v[36:37], v[40:41], v[54:55] op_sel_hi:[1,0]
	v_pk_fma_f32 v[34:35], v[10:11], v[34:35], v[14:15]
	v_pk_fma_f32 v[36:37], v[12:13], v[36:37], v[16:17]
	s_waitcnt vmcnt(6)
	v_pk_add_f32 v[40:41], v[90:91], 1.0 op_sel_hi:[1,0]
	global_store_dwordx4 v[74:75], v[34:37], off offset:1024 nt
	v_pk_add_f32 v[38:39], v[92:93], 1.0 op_sel_hi:[1,0]
	v_add_u32_e32 v50, s13, v50
	v_pk_fma_f32 v[34:35], v[40:41], v[34:35], v[86:87]
	v_pk_fma_f32 v[36:37], v[38:39], v[36:37], v[88:89]
	s_nop 0
	s_nop 0
	s_nop 0
	s_nop 0
	s_nop 0
	v_cvt_pk_bf16_f32 v34, v34, v35
	s_nop 0
	s_nop 0
	s_nop 0
	s_nop 0
	s_nop 0
	v_cvt_pk_bf16_f32 v35, v36, v37
	global_store_dwordx2 v[76:77], v[34:35], off offset:512 nt
	v_pk_mul_f32 v[34:35], v[42:43], v[54:55] op_sel_hi:[1,0]
	v_pk_mul_f32 v[36:37], v[44:45], v[54:55] op_sel_hi:[1,0]
	v_pk_fma_f32 v[34:35], v[18:19], v[34:35], v[22:23]
	v_pk_fma_f32 v[36:37], v[20:21], v[36:37], v[24:25]
	s_waitcnt vmcnt(6)
	v_pk_add_f32 v[40:41], v[98:99], 1.0 op_sel_hi:[1,0]
	global_store_dwordx4 v[74:75], v[34:37], off offset:2048 nt
	v_pk_add_f32 v[38:39], v[100:101], 1.0 op_sel_hi:[1,0]
	v_cmp_lt_i32_e32 vcc, s24, v50
	v_pk_fma_f32 v[34:35], v[40:41], v[34:35], v[94:95]
	v_pk_fma_f32 v[36:37], v[38:39], v[36:37], v[96:97]
	s_nop 0
	s_nop 0
	s_nop 0
	s_nop 0
	s_nop 0
	v_cvt_pk_bf16_f32 v34, v34, v35
	s_nop 0
	s_nop 0
	s_nop 0
	s_nop 0
	s_nop 0
	v_cvt_pk_bf16_f32 v35, v36, v37
	global_store_dwordx2 v[76:77], v[34:35], off offset:1024 nt
	v_pk_mul_f32 v[34:35], v[46:47], v[54:55] op_sel_hi:[1,0]
	v_pk_mul_f32 v[36:37], v[48:49], v[54:55] op_sel_hi:[1,0]
	v_pk_fma_f32 v[34:35], v[26:27], v[34:35], v[30:31]
	v_pk_fma_f32 v[36:37], v[28:29], v[36:37], v[32:33]
	s_waitcnt vmcnt(7)
	v_pk_add_f32 v[40:41], v[102:103], 1.0 op_sel_hi:[1,0]
	global_store_dwordx4 v[74:75], v[34:37], off offset:3072 nt
	v_pk_add_f32 v[38:39], v[104:105], 1.0 op_sel_hi:[1,0]
	s_or_b64 s[10:11], vcc, s[10:11]
	s_waitcnt vmcnt(7)
	v_pk_fma_f32 v[34:35], v[40:41], v[34:35], v[106:107]
	v_pk_fma_f32 v[36:37], v[38:39], v[36:37], v[108:109]
	s_nop 0
	s_nop 0
	s_nop 0
	s_nop 0
	s_nop 0
	v_cvt_pk_bf16_f32 v34, v34, v35
	s_nop 0
	s_nop 0
	s_nop 0
	s_nop 0
	s_nop 0
	v_cvt_pk_bf16_f32 v35, v36, v37
	global_store_dwordx2 v[76:77], v[34:35], off offset:1536 nt
	s_andn2_b64 exec, exec, s[10:11]
	s_cbranch_execz .LBB0_1070

.LBB0_1366:
	s_or_b64 exec, exec, s[2:3]
	s_waitcnt vmcnt(0)
	v_add_f32_e32 v54, v34, v35
	v_add_f32_e32 v69, v36, v37
	v_add_f32_e32 v54, v54, v69
	v_add_f32_e32 v69, v38, v39
	v_add_f32_e32 v71, v40, v41
	v_add_f32_e32 v54, 0, v54
	v_add_f32_e32 v69, v69, v71
	v_add_f32_e32 v54, v54, v69
	v_add_f32_e32 v69, v42, v43
	v_add_f32_e32 v71, v44, v45
	v_mov_b32_e32 v78, v47
	v_mov_b32_e32 v79, v48
	v_mov_b32_e32 v80, v46
	v_mov_b32_e32 v81, v49
	v_add_f32_e32 v69, v69, v71
	v_pk_add_f32 v[78:79], v[78:79], v[80:81]
	v_add_f32_e32 v54, v54, v69
	v_add_f32_e32 v69, v78, v79
	v_add_f32_e32 v54, v54, v69
	v_cmp_gt_i32_e32 vcc, s24, v50
	v_mov_b32_e32 v77, v55
	v_add_f32_dpp v54, v54, v54 quad_perm:[1,0,3,2] row_mask:0xf bank_mask:0xf bound_ctrl:1
	v_mov_b32_e32 v73, v55
	v_lshl_add_u64 v[74:75], v[64:65], 0, v[74:75]
	v_add_f32_dpp v54, v54, v54 quad_perm:[2,3,0,1] row_mask:0xf bank_mask:0xf bound_ctrl:1
	s_nop 1
	v_add_f32_dpp v54, v54, v54 row_ror:4 row_mask:0xf bank_mask:0xf bound_ctrl:1
	s_nop 1
	v_add_f32_dpp v54, v54, v54 row_ror:8 row_mask:0xf bank_mask:0xf bound_ctrl:1
	ds_bpermute_b32 v69, v1, v54
	s_waitcnt lgkmcnt(0)
	v_add_f32_e32 v54, v54, v69
	ds_bpermute_b32 v69, v53, v54
	s_waitcnt lgkmcnt(0)
	v_add_f32_e32 v71, v54, v69
	v_cndmask_b32_e64 v54, v85, 0, vcc
	v_lshl_add_u64 v[86:87], s[12:13], 0, v[54:55]
	v_lshl_add_u64 v[106:107], v[86:87], 0, s[16:17]
	v_lshl_add_u64 v[78:79], v[106:107], 0, v[76:77]
	global_load_dwordx4 v[78:81], v[78:79], off
	v_lshl_add_u64 v[76:77], v[86:87], 0, v[76:77]
	global_load_dwordx4 v[86:89], v[76:77], off
	v_fmamk_f32 v35, v71, 0xba800000, v35
	v_fmamk_f32 v34, v71, 0xba800000, v34
	v_fmamk_f32 v37, v71, 0xba800000, v37
	v_fmac_f32_e32 v36, 0xba800000, v71
	v_pk_mul_f32 v[82:83], v[36:37], v[36:37]
	v_pk_mul_f32 v[90:91], v[34:35], v[34:35]
	v_fmamk_f32 v39, v71, 0xba800000, v39
	v_pk_mov_b32 v[92:93], v[90:91], v[82:83] op_sel:[1,0]
	v_mov_b32_e32 v91, v83
	v_fmamk_f32 v38, v71, 0xba800000, v38
	v_fmamk_f32 v41, v71, 0xba800000, v41
	v_fmac_f32_e32 v40, 0xba800000, v71
	v_pk_add_f32 v[82:83], v[92:93], v[90:91]
	v_pk_mul_f32 v[90:91], v[40:41], v[40:41]
	v_pk_mul_f32 v[92:93], v[38:39], v[38:39]
	v_mov_b32_e32 v69, v55
	v_pk_mov_b32 v[94:95], v[92:93], v[90:91] op_sel:[1,0]
	v_mov_b32_e32 v93, v91
	v_pk_add_f32 v[90:91], v[94:95], v[92:93]
	global_load_dwordx4 v[94:97], v[76:77], off offset:1024
	v_pk_add_f32 v[98:99], v[90:91], v[90:91] op_sel_hi:[0,1]
	v_lshl_add_u64 v[90:91], v[106:107], 0, v[68:69]
	global_load_dwordx4 v[90:93], v[90:91], off
	v_fmamk_f32 v42, v71, 0xba800000, v42
	v_fmamk_f32 v43, v71, 0xba800000, v43
	v_fmac_f32_e32 v44, 0xba800000, v71
	v_mul_f32_e32 v54, v42, v42
	v_fmamk_f32 v45, v71, 0xba800000, v45
	v_pk_fma_f32 v[100:101], v[42:43], v[42:43], v[54:55] op_sel_hi:[1,1,0]
	v_mul_f32_e32 v54, v44, v44
	v_pk_add_f32 v[82:83], v[82:83], v[82:83] op_sel_hi:[0,1]
	v_pk_fma_f32 v[102:103], v[44:45], v[44:45], v[54:55] op_sel_hi:[1,1,0]
	v_fmamk_f32 v49, v71, 0xba800000, v49
	v_fmamk_f32 v48, v71, 0xba800000, v48
	v_fmamk_f32 v47, v71, 0xba800000, v47
	v_fmac_f32_e32 v46, 0xba800000, v71
	v_mul_f32_e32 v100, v46, v46
	v_mul_f32_e32 v102, v47, v47
	v_mul_f32_e32 v82, v48, v48
	v_mul_f32_e32 v98, v49, v49
	v_pk_add_f32 v[100:101], v[100:101], v[102:103]
	v_pk_add_f32 v[82:83], v[82:83], v[98:99]
	v_mov_b32_e32 v71, v55
	v_pk_add_f32 v[82:83], v[100:101], v[82:83]
	global_load_dwordx4 v[102:105], v[76:77], off offset:2048
	v_add_f32_e32 v54, v82, v83
	v_lshl_add_u64 v[82:83], v[106:107], 0, v[70:71]
	global_load_dwordx4 v[98:101], v[82:83], off
	v_lshl_add_u64 v[82:83], v[106:107], 0, v[72:73]
	global_load_dwordx4 v[106:109], v[82:83], off
	global_load_dwordx4 v[110:113], v[76:77], off offset:3072
	v_add_f32_dpp v54, v54, v54 quad_perm:[1,0,3,2] row_mask:0xf bank_mask:0xf bound_ctrl:1
	s_waitcnt vmcnt(7)
	v_pk_add_f32 v[78:79], v[78:79], 1.0 op_sel_hi:[1,0]
	v_add_f32_dpp v54, v54, v54 quad_perm:[2,3,0,1] row_mask:0xf bank_mask:0xf bound_ctrl:1
	v_pk_add_f32 v[76:77], v[80:81], 1.0 op_sel_hi:[1,0]
	s_nop 0
	v_add_f32_dpp v54, v54, v54 row_ror:4 row_mask:0xf bank_mask:0xf bound_ctrl:1
	s_nop 1
	v_add_f32_dpp v54, v54, v54 row_ror:8 row_mask:0xf bank_mask:0xf bound_ctrl:1
	ds_bpermute_b32 v69, v1, v54
	s_waitcnt lgkmcnt(0)
	v_add_f32_e32 v54, v54, v69
	ds_bpermute_b32 v69, v53, v54
	s_waitcnt lgkmcnt(0)
	v_add_f32_e32 v54, v54, v69
	v_fmamk_f32 v54, v54, 0x3a800000, v84
	v_mul_f32_e32 v69, 0x4b800000, v54
	v_cmp_gt_f32_e32 vcc, s25, v54
	s_nop 1
	v_cndmask_b32_e32 v54, v54, v69, vcc
	v_rsq_f32_e32 v54, v54
	s_nop 0
	v_mul_f32_e32 v69, 0x45800000, v54
	v_cndmask_b32_e32 v54, v54, v69, vcc
	v_pk_mul_f32 v[34:35], v[34:35], v[54:55] op_sel_hi:[1,0]
	v_pk_mul_f32 v[36:37], v[36:37], v[54:55] op_sel_hi:[1,0]
	v_pk_fma_f32 v[34:35], v[2:3], v[34:35], v[6:7]
	v_pk_fma_f32 v[36:37], v[4:5], v[36:37], v[8:9]
	global_store_dwordx4 v[74:75], v[34:37], off nt
	s_waitcnt vmcnt(7)
	s_nop 0
	v_pk_fma_f32 v[34:35], v[78:79], v[34:35], v[86:87]
	v_pk_fma_f32 v[36:37], v[76:77], v[36:37], v[88:89]
	s_nop 0
	s_nop 0
	s_nop 0
	s_nop 0
	s_nop 0
	v_cvt_pk_bf16_f32 v34, v34, v35
	s_nop 0
	s_nop 0
	s_nop 0
	s_nop 0
	s_nop 0
	v_cvt_pk_bf16_f32 v35, v36, v37
	v_lshlrev_b64 v[36:37], 11, v[50:51]
	v_lshl_add_u64 v[76:77], v[66:67], 0, v[36:37]
	global_store_dwordx2 v[76:77], v[34:35], off nt
	v_pk_mul_f32 v[34:35], v[38:39], v[54:55] op_sel_hi:[1,0]
	v_pk_mul_f32 v[36:37], v[40:41], v[54:55] op_sel_hi:[1,0]
	v_pk_fma_f32 v[34:35], v[10:11], v[34:35], v[14:15]
	v_pk_fma_f32 v[36:37], v[12:13], v[36:37], v[16:17]
	s_waitcnt vmcnt(6)
	v_pk_add_f32 v[40:41], v[90:91], 1.0 op_sel_hi:[1,0]
	global_store_dwordx4 v[74:75], v[34:37], off offset:1024 nt
	v_pk_add_f32 v[38:39], v[92:93], 1.0 op_sel_hi:[1,0]
	v_add_u32_e32 v50, s21, v50
	v_pk_fma_f32 v[34:35], v[40:41], v[34:35], v[94:95]
	v_pk_fma_f32 v[36:37], v[38:39], v[36:37], v[96:97]
	s_nop 0
	s_nop 0
	s_nop 0
	s_nop 0
	s_nop 0
	v_cvt_pk_bf16_f32 v34, v34, v35
	s_nop 0
	s_nop 0
	s_nop 0
	s_nop 0
	s_nop 0
	v_cvt_pk_bf16_f32 v35, v36, v37
	global_store_dwordx2 v[76:77], v[34:35], off offset:512 nt
	v_pk_mul_f32 v[34:35], v[42:43], v[54:55] op_sel_hi:[1,0]
	v_pk_mul_f32 v[36:37], v[44:45], v[54:55] op_sel_hi:[1,0]
	v_pk_fma_f32 v[34:35], v[18:19], v[34:35], v[22:23]
	v_pk_fma_f32 v[36:37], v[20:21], v[36:37], v[24:25]
	s_waitcnt vmcnt(6)
	v_pk_add_f32 v[40:41], v[98:99], 1.0 op_sel_hi:[1,0]
	global_store_dwordx4 v[74:75], v[34:37], off offset:2048 nt
	v_pk_add_f32 v[38:39], v[100:101], 1.0 op_sel_hi:[1,0]
	v_cmp_lt_i32_e32 vcc, s28, v50
	v_pk_fma_f32 v[34:35], v[40:41], v[34:35], v[102:103]
	v_pk_fma_f32 v[36:37], v[38:39], v[36:37], v[104:105]
	s_nop 0
	s_nop 0
	s_nop 0
	s_nop 0
	s_nop 0
	v_cvt_pk_bf16_f32 v34, v34, v35
	s_nop 0
	s_nop 0
	s_nop 0
	s_nop 0
	s_nop 0
	v_cvt_pk_bf16_f32 v35, v36, v37
	global_store_dwordx2 v[76:77], v[34:35], off offset:1024 nt
	v_pk_mul_f32 v[34:35], v[46:47], v[54:55] op_sel_hi:[1,0]
	v_pk_mul_f32 v[36:37], v[48:49], v[54:55] op_sel_hi:[1,0]
	v_pk_fma_f32 v[34:35], v[26:27], v[34:35], v[30:31]
	v_pk_fma_f32 v[36:37], v[28:29], v[36:37], v[32:33]
	s_waitcnt vmcnt(7)
	v_pk_add_f32 v[40:41], v[106:107], 1.0 op_sel_hi:[1,0]
	global_store_dwordx4 v[74:75], v[34:37], off offset:3072 nt
	v_pk_add_f32 v[38:39], v[108:109], 1.0 op_sel_hi:[1,0]
	s_or_b64 s[18:19], vcc, s[18:19]
	s_waitcnt vmcnt(7)
	v_pk_fma_f32 v[34:35], v[40:41], v[34:35], v[110:111]
	v_pk_fma_f32 v[36:37], v[38:39], v[36:37], v[112:113]
	s_nop 0
	s_nop 0
	s_nop 0
	s_nop 0
	s_nop 0
	v_cvt_pk_bf16_f32 v34, v34, v35
	s_nop 0
	s_nop 0
	s_nop 0
	s_nop 0
	s_nop 0
	v_cvt_pk_bf16_f32 v35, v36, v37
	global_store_dwordx2 v[76:77], v[34:35], off offset:1536 nt
	s_andn2_b64 exec, exec, s[18:19]
	s_cbranch_execz .LBB0_1383

.LBB0_1847:
	v_ashrrev_i32_e32 v55, 31, v54
	v_lshlrev_b64 v[92:93], 12, v[54:55]
	v_lshl_add_u64 v[94:95], v[56:57], 0, v[92:93]
	global_load_dwordx4 v[80:83], v[94:95], off
	global_load_dwordx4 v[84:87], v[94:95], off offset:1024
	global_load_dwordx4 v[88:91], v[94:95], off offset:2048
	global_load_dwordx4 v[50:53], v[94:95], off offset:3072
	v_lshl_add_u64 v[92:93], v[58:59], 0, v[92:93]
	s_waitcnt vmcnt(3)
	v_mov_b32_e32 v94, v81
	v_mov_b32_e32 v95, v82
	v_mov_b32_e32 v96, v80
	v_mov_b32_e32 v97, v83
	s_waitcnt vmcnt(2)
	v_mov_b32_e32 v98, v85
	v_mov_b32_e32 v99, v86
	v_mov_b32_e32 v100, v84
	v_mov_b32_e32 v101, v87
	v_pk_add_f32 v[94:95], v[94:95], v[96:97]
	v_pk_add_f32 v[96:97], v[98:99], v[100:101]
	v_add_f32_e32 v100, v94, v95
	v_pk_add_f32 v[94:95], v[96:97], v[96:97] op_sel:[0,1] op_sel_hi:[1,0]
	s_waitcnt vmcnt(1)
	v_add_f32_e32 v102, v88, v89
	v_add_f32_e32 v104, v90, v91
	s_waitcnt vmcnt(0)
	v_mov_b32_e32 v107, v50
	v_mov_b32_e32 v103, v52
	v_mov_b32_e32 v105, v53
	v_add_f32_e32 v106, 0, v100
	v_mov_b32_e32 v95, v51
	v_pk_add_f32 v[98:99], v[102:103], v[104:105]
	v_pk_add_f32 v[94:95], v[106:107], v[94:95]
	s_nop 0
	v_pk_add_f32 v[94:95], v[94:95], v[98:99]
	s_nop 0
	v_add_f32_e32 v94, v94, v95
	s_nop 1
	v_add_f32_dpp v94, v94, v94 quad_perm:[1,0,3,2] row_mask:0xf bank_mask:0xf bound_ctrl:1
	s_nop 1
	v_add_f32_dpp v94, v94, v94 quad_perm:[2,3,0,1] row_mask:0xf bank_mask:0xf bound_ctrl:1
	s_nop 1
	v_add_f32_dpp v94, v94, v94 row_ror:4 row_mask:0xf bank_mask:0xf bound_ctrl:1
	s_nop 1
	v_add_f32_dpp v94, v94, v94 row_ror:8 row_mask:0xf bank_mask:0xf bound_ctrl:1
	ds_bpermute_b32 v95, v78, v94
	s_waitcnt lgkmcnt(0)
	v_add_f32_e32 v94, v94, v95
	ds_bpermute_b32 v95, v79, v94
	s_waitcnt lgkmcnt(0)
	v_add_f32_e32 v94, v94, v95
	v_fmamk_f32 v81, v94, 0xba800000, v81
	v_fmamk_f32 v80, v94, 0xba800000, v80
	v_fmamk_f32 v83, v94, 0xba800000, v83
	v_fmac_f32_e32 v82, 0xba800000, v94
	v_fmamk_f32 v85, v94, 0xba800000, v85
	v_fmamk_f32 v84, v94, 0xba800000, v84
	v_fmamk_f32 v87, v94, 0xba800000, v87
	v_fmac_f32_e32 v86, 0xba800000, v94
	v_fmamk_f32 v89, v94, 0xba800000, v89
	v_fmamk_f32 v88, v94, 0xba800000, v88
	v_fmamk_f32 v91, v94, 0xba800000, v91
	v_fmac_f32_e32 v90, 0xba800000, v94
	v_fmamk_f32 v53, v94, 0xba800000, v53
	v_fmamk_f32 v52, v94, 0xba800000, v52
	v_fmamk_f32 v51, v94, 0xba800000, v51
	v_fmac_f32_e32 v50, 0xba800000, v94
	v_pk_mul_f32 v[94:95], v[82:83], v[82:83]
	v_pk_mul_f32 v[96:97], v[80:81], v[80:81]
	v_pk_mul_f32 v[98:99], v[86:87], v[86:87]
	v_pk_mul_f32 v[100:101], v[84:85], v[84:85]
	v_pk_mov_b32 v[106:107], v[96:97], v[94:95] op_sel:[1,0]
	v_mov_b32_e32 v97, v95
	v_pk_mov_b32 v[94:95], v[100:101], v[98:99] op_sel:[1,0]
	v_mov_b32_e32 v101, v99
	v_mul_f32_e32 v102, v88, v88
	v_mul_f32_e32 v104, v90, v90
	v_pk_add_f32 v[96:97], v[106:107], v[96:97]
	v_pk_add_f32 v[94:95], v[94:95], v[100:101]
	v_pk_fma_f32 v[98:99], v[88:89], v[88:89], v[102:103] op_sel_hi:[1,1,0]
	v_pk_fma_f32 v[102:103], v[90:91], v[90:91], v[104:105] op_sel_hi:[1,1,0]
	v_pk_add_f32 v[96:97], v[96:97], v[96:97] op_sel_hi:[0,1]
	v_pk_add_f32 v[94:95], v[94:95], v[94:95] op_sel_hi:[0,1]
	v_mul_f32_e32 v98, v50, v50
	v_mul_f32_e32 v102, v51, v51
	v_mul_f32_e32 v96, v52, v52
	v_mul_f32_e32 v94, v53, v53
	v_pk_add_f32 v[98:99], v[98:99], v[102:103]
	v_pk_add_f32 v[94:95], v[96:97], v[94:95]
	s_nop 0
	v_pk_add_f32 v[94:95], v[98:99], v[94:95]
	s_nop 0
	v_add_f32_e32 v94, v94, v95
	s_nop 1
	v_add_f32_dpp v94, v94, v94 quad_perm:[1,0,3,2] row_mask:0xf bank_mask:0xf bound_ctrl:1
	s_nop 1
	v_add_f32_dpp v94, v94, v94 quad_perm:[2,3,0,1] row_mask:0xf bank_mask:0xf bound_ctrl:1
	s_nop 1
	v_add_f32_dpp v94, v94, v94 row_ror:4 row_mask:0xf bank_mask:0xf bound_ctrl:1
	s_nop 1
	v_add_f32_dpp v94, v94, v94 row_ror:8 row_mask:0xf bank_mask:0xf bound_ctrl:1
	ds_bpermute_b32 v95, v78, v94
	s_waitcnt lgkmcnt(0)
	v_add_f32_e32 v94, v94, v95
	ds_bpermute_b32 v95, v79, v94
	s_waitcnt lgkmcnt(0)
	v_add_f32_e32 v94, v94, v95
	v_fmamk_f32 v94, v94, 0x3a800000, v1
	v_mul_f32_e32 v95, 0x4b800000, v94
	v_cmp_gt_f32_e32 vcc, s11, v94
	s_nop 1
	v_cndmask_b32_e32 v94, v94, v95, vcc
	v_rsq_f32_e32 v96, v94
	v_lshlrev_b64 v[94:95], 11, v[54:55]
	v_lshl_add_u64 v[94:95], v[60:61], 0, v[94:95]
	v_add_u32_e32 v54, s10, v54
	v_mul_f32_e32 v55, 0x45800000, v96
	v_cndmask_b32_e32 v96, v96, v55, vcc
	v_pk_mul_f32 v[80:81], v[80:81], v[96:97] op_sel_hi:[1,0]
	v_pk_mul_f32 v[82:83], v[82:83], v[96:97] op_sel_hi:[1,0]
	v_pk_mul_f32 v[84:85], v[84:85], v[96:97] op_sel_hi:[1,0]
	v_pk_mul_f32 v[86:87], v[86:87], v[96:97] op_sel_hi:[1,0]
	v_pk_fma_f32 v[82:83], v[4:5], v[82:83], v[8:9]
	v_pk_fma_f32 v[80:81], v[2:3], v[80:81], v[6:7]
	v_pk_fma_f32 v[86:87], v[12:13], v[86:87], v[16:17]
	v_pk_fma_f32 v[84:85], v[10:11], v[84:85], v[14:15]
	global_store_dwordx4 v[92:93], v[80:83], off nt
	v_pk_mul_f32 v[88:89], v[88:89], v[96:97] op_sel_hi:[1,0]
	v_pk_mul_f32 v[90:91], v[90:91], v[96:97] op_sel_hi:[1,0]
	v_pk_fma_f32 v[82:83], v[62:63], v[82:83], v[20:21]
	v_pk_fma_f32 v[80:81], v[64:65], v[80:81], v[18:19]
	global_store_dwordx4 v[92:93], v[84:87], off offset:1024 nt
	v_bfe_u32 v55, v80, 16, 1
	v_bfe_u32 v97, v81, 16, 1
	v_pk_fma_f32 v[86:87], v[66:67], v[86:87], v[24:25]
	v_pk_fma_f32 v[84:85], v[68:69], v[84:85], v[22:23]
	v_bfe_u32 v98, v82, 16, 1
	v_pk_fma_f32 v[90:91], v[36:37], v[90:91], v[40:41]
	v_pk_fma_f32 v[88:89], v[34:35], v[88:89], v[38:39]
	v_bfe_u32 v99, v83, 16, 1
	v_bfe_u32 v100, v84, 16, 1
	v_bfe_u32 v101, v85, 16, 1
	s_nop 0
	v_add3_u32 v55, v80, v55, s12
	v_add3_u32 v80, v81, v97, s12
	v_add3_u32 v81, v82, v98, s12
	global_store_dwordx4 v[92:93], v[88:91], off offset:2048 nt
	s_nop 0
	v_add3_u32 v82, v83, v99, s12
	v_pk_fma_f32 v[90:91], v[70:71], v[90:91], v[28:29]
	v_add3_u32 v83, v84, v100, s12
	v_add3_u32 v84, v85, v101, s12
	s_nop 0
	v_lshrrev_b32_e32 v55, 16, v55
	v_lshrrev_b32_e32 v81, 16, v81
	s_nop 0
	v_lshrrev_b32_e32 v83, 16, v83
	s_nop 0
	v_and_or_b32 v80, v80, s13, v55
	v_and_or_b32 v81, v82, s13, v81
	s_nop 0
	v_pk_mul_f32 v[50:51], v[50:51], v[96:97] op_sel_hi:[1,0]
	v_pk_mul_f32 v[52:53], v[52:53], v[96:97] op_sel_hi:[1,0]
	v_and_or_b32 v82, v84, s13, v83
	v_cvt_pk_bf16_f32 v83, v86, v87
	global_store_dwordx2 v[94:95], v[80:81], off nt
	global_store_dwordx2 v[94:95], v[82:83], off offset:512 nt
	s_nop 0
	s_nop 0
	v_pk_fma_f32 v[52:53], v[44:45], v[52:53], v[48:49]
	v_pk_fma_f32 v[50:51], v[42:43], v[50:51], v[46:47]
	s_nop 0
	s_nop 0
	global_store_dwordx4 v[92:93], v[50:53], off offset:3072 nt
	v_cvt_pk_bf16_f32 v81, v90, v91
	v_pk_fma_f32 v[88:89], v[72:73], v[88:89], v[26:27]
	v_pk_fma_f32 v[50:51], v[76:77], v[50:51], v[30:31]
	v_pk_fma_f32 v[52:53], v[74:75], v[52:53], v[32:33]
	s_nop 0
	s_nop 0
	s_nop 0
	s_nop 0
	s_nop 0
	s_nop 0
	v_cvt_pk_bf16_f32 v50, v50, v51
	s_nop 0
	s_nop 0
	s_nop 0
	s_nop 0
	s_nop 0
	s_nop 0
	s_nop 0
	s_nop 0
	s_nop 0
	v_cmp_lt_i32_e32 vcc, s14, v54
	v_cvt_pk_bf16_f32 v80, v88, v89
	v_cvt_pk_bf16_f32 v51, v52, v53
	s_or_b64 s[4:5], vcc, s[4:5]
	global_store_dwordx2 v[94:95], v[80:81], off offset:1024 nt
	global_store_dwordx2 v[94:95], v[50:51], off offset:1536 nt
	s_andn2_b64 exec, exec, s[4:5]
	s_cbranch_execnz .LBB0_1847

.LBB0_2130:
	v_ashrrev_i32_e32 v33, 31, v32
	v_lshlrev_b64 v[58:59], 12, v[32:33]
	v_lshl_add_u64 v[60:61], v[34:35], 0, v[58:59]
	global_load_dwordx4 v[42:45], v[60:61], off
	global_load_dwordx4 v[46:49], v[60:61], off offset:1024
	global_load_dwordx4 v[50:53], v[60:61], off offset:2048
	global_load_dwordx4 v[54:57], v[60:61], off offset:3072
	v_add_u32_e32 v32, s4, v32
	v_cmp_lt_i32_e64 s[0:1], s6, v32
	v_lshl_add_u64 v[58:59], v[36:37], 0, v[58:59]
	s_or_b64 s[2:3], s[0:1], s[2:3]
	s_waitcnt vmcnt(0)
	v_mov_b32_e32 v60, v43
	v_mov_b32_e32 v61, v44
	v_mov_b32_e32 v62, v42
	v_mov_b32_e32 v63, v45
	v_mov_b32_e32 v64, v47
	v_mov_b32_e32 v65, v48
	v_mov_b32_e32 v66, v46
	v_mov_b32_e32 v67, v49
	v_pk_add_f32 v[60:61], v[60:61], v[62:63]
	v_pk_add_f32 v[62:63], v[64:65], v[66:67]
	v_add_f32_e32 v33, v60, v61
	v_pk_add_f32 v[60:61], v[62:63], v[62:63] op_sel:[0,1] op_sel_hi:[1,0]
	v_add_f32_e32 v68, v50, v51
	v_add_f32_e32 v70, v52, v53
	v_mov_b32_e32 v73, v54
	v_mov_b32_e32 v69, v56
	v_mov_b32_e32 v71, v57
	v_add_f32_e32 v72, 0, v33
	v_mov_b32_e32 v61, v55
	v_pk_add_f32 v[64:65], v[68:69], v[70:71]
	v_pk_add_f32 v[60:61], v[72:73], v[60:61]
	s_nop 0
	v_pk_add_f32 v[60:61], v[60:61], v[64:65]
	s_nop 0
	v_add_f32_e32 v33, v60, v61
	s_nop 1
	v_add_f32_dpp v33, v33, v33 quad_perm:[1,0,3,2] row_mask:0xf bank_mask:0xf bound_ctrl:1
	s_nop 1
	v_add_f32_dpp v33, v33, v33 quad_perm:[2,3,0,1] row_mask:0xf bank_mask:0xf bound_ctrl:1
	s_nop 1
	v_add_f32_dpp v33, v33, v33 row_ror:4 row_mask:0xf bank_mask:0xf bound_ctrl:1
	s_nop 1
	v_add_f32_dpp v33, v33, v33 row_ror:8 row_mask:0xf bank_mask:0xf bound_ctrl:1
	ds_bpermute_b32 v41, v38, v33
	s_waitcnt lgkmcnt(0)
	v_add_f32_e32 v33, v33, v41
	ds_bpermute_b32 v41, v39, v33
	s_waitcnt lgkmcnt(0)
	v_add_f32_e32 v33, v33, v41
	v_fmamk_f32 v43, v33, 0xba800000, v43
	v_fmamk_f32 v42, v33, 0xba800000, v42
	v_fmamk_f32 v45, v33, 0xba800000, v45
	v_fmac_f32_e32 v44, 0xba800000, v33
	v_fmamk_f32 v47, v33, 0xba800000, v47
	v_fmamk_f32 v46, v33, 0xba800000, v46
	v_fmamk_f32 v49, v33, 0xba800000, v49
	v_fmac_f32_e32 v48, 0xba800000, v33
	v_pk_mul_f32 v[60:61], v[44:45], v[44:45]
	v_pk_mul_f32 v[62:63], v[42:43], v[42:43]
	v_pk_mul_f32 v[64:65], v[48:49], v[48:49]
	v_pk_mul_f32 v[66:67], v[46:47], v[46:47]
	v_fmamk_f32 v50, v33, 0xba800000, v50
	v_fmac_f32_e32 v52, 0xba800000, v33
	v_pk_mov_b32 v[72:73], v[62:63], v[60:61] op_sel:[1,0]
	v_mov_b32_e32 v63, v61
	v_pk_mov_b32 v[60:61], v[66:67], v[64:65] op_sel:[1,0]
	v_mov_b32_e32 v67, v65
	v_fmamk_f32 v51, v33, 0xba800000, v51
	v_fmamk_f32 v53, v33, 0xba800000, v53
	v_mul_f32_e32 v68, v50, v50
	v_mul_f32_e32 v70, v52, v52
	v_pk_add_f32 v[62:63], v[72:73], v[62:63]
	v_pk_add_f32 v[60:61], v[60:61], v[66:67]
	v_fmamk_f32 v57, v33, 0xba800000, v57
	v_fmamk_f32 v56, v33, 0xba800000, v56
	v_fmamk_f32 v55, v33, 0xba800000, v55
	v_fmac_f32_e32 v54, 0xba800000, v33
	v_pk_fma_f32 v[64:65], v[50:51], v[50:51], v[68:69] op_sel_hi:[1,1,0]
	v_pk_fma_f32 v[68:69], v[52:53], v[52:53], v[70:71] op_sel_hi:[1,1,0]
	v_pk_add_f32 v[62:63], v[62:63], v[62:63] op_sel_hi:[0,1]
	v_pk_add_f32 v[60:61], v[60:61], v[60:61] op_sel_hi:[0,1]
	v_mul_f32_e32 v64, v54, v54
	v_mul_f32_e32 v68, v55, v55
	v_mul_f32_e32 v62, v56, v56
	v_mul_f32_e32 v60, v57, v57
	v_pk_add_f32 v[64:65], v[64:65], v[68:69]
	v_pk_add_f32 v[60:61], v[62:63], v[60:61]
	s_nop 0
	v_pk_add_f32 v[60:61], v[64:65], v[60:61]
	s_nop 0
	v_add_f32_e32 v33, v60, v61
	s_nop 1
	v_add_f32_dpp v33, v33, v33 quad_perm:[1,0,3,2] row_mask:0xf bank_mask:0xf bound_ctrl:1
	s_nop 1
	v_add_f32_dpp v33, v33, v33 quad_perm:[2,3,0,1] row_mask:0xf bank_mask:0xf bound_ctrl:1
	s_nop 1
	v_add_f32_dpp v33, v33, v33 row_ror:4 row_mask:0xf bank_mask:0xf bound_ctrl:1
	s_nop 1
	v_add_f32_dpp v33, v33, v33 row_ror:8 row_mask:0xf bank_mask:0xf bound_ctrl:1
	ds_bpermute_b32 v41, v38, v33
	s_waitcnt lgkmcnt(0)
	v_add_f32_e32 v33, v33, v41
	ds_bpermute_b32 v41, v39, v33
	s_waitcnt lgkmcnt(0)
	v_add_f32_e32 v33, v33, v41
	v_fmamk_f32 v33, v33, 0x3a800000, v40
	v_mul_f32_e32 v41, 0x4b800000, v33
	v_cmp_gt_f32_e32 vcc, s5, v33
	s_nop 1
	v_cndmask_b32_e32 v33, v33, v41, vcc
	v_rsq_f32_e32 v33, v33
	s_nop 0
	v_mul_f32_e32 v41, 0x45800000, v33
	v_cndmask_b32_e32 v60, v33, v41, vcc
	v_pk_mul_f32 v[42:43], v[42:43], v[60:61] op_sel_hi:[1,0]
	v_pk_mul_f32 v[44:45], v[44:45], v[60:61] op_sel_hi:[1,0]
	v_pk_mul_f32 v[46:47], v[46:47], v[60:61] op_sel_hi:[1,0]
	v_pk_mul_f32 v[48:49], v[48:49], v[60:61] op_sel_hi:[1,0]
	v_pk_mul_f32 v[50:51], v[50:51], v[60:61] op_sel_hi:[1,0]
	v_pk_mul_f32 v[52:53], v[52:53], v[60:61] op_sel_hi:[1,0]
	v_pk_mul_f32 v[54:55], v[54:55], v[60:61] op_sel_hi:[1,0]
	v_pk_mul_f32 v[56:57], v[56:57], v[60:61] op_sel_hi:[1,0]
	v_pk_fma_f32 v[44:45], v[2:3], v[44:45], v[6:7]
	v_pk_fma_f32 v[42:43], v[0:1], v[42:43], v[4:5]
	v_pk_fma_f32 v[48:49], v[10:11], v[48:49], v[14:15]
	v_pk_fma_f32 v[46:47], v[8:9], v[46:47], v[12:13]
	v_pk_fma_f32 v[52:53], v[18:19], v[52:53], v[22:23]
	v_pk_fma_f32 v[50:51], v[16:17], v[50:51], v[20:21]
	v_pk_fma_f32 v[56:57], v[26:27], v[56:57], v[30:31]
	v_pk_fma_f32 v[54:55], v[24:25], v[54:55], v[28:29]
	global_store_dwordx4 v[58:59], v[42:45], off nt
	global_store_dwordx4 v[58:59], v[46:49], off offset:1024 nt
	global_store_dwordx4 v[58:59], v[50:53], off offset:2048 nt
	global_store_dwordx4 v[58:59], v[54:57], off offset:3072 nt
	s_andn2_b64 exec, exec, s[2:3]
	s_cbranch_execnz .LBB0_2130
